# speedup vs baseline: 1.9472x; 1.9472x over previous
.LBB0_2677:
	v_readlane_b32 s0, v255, 2
	v_readlane_b32 s1, v255, 3
	s_cmp_lg_u32 s2, s0
	s_mov_b64 s[0:1], -1
	s_cbranch_scc0 .LBB0_2699
	s_waitcnt vmcnt(0)
	s_waitcnt vmcnt(0) lgkmcnt(0)
	s_barrier
	s_mov_b64 s[0:1], exec
	v_readlane_b32 s2, v255, 4
	v_readlane_b32 s3, v255, 5
	s_and_b64 s[2:3], s[0:1], s[2:3]
	s_mov_b64 exec, s[2:3]
	s_cbranch_execz .LBB0_2698
	s_mov_b64 s[6:7], exec
	v_mbcnt_lo_u32_b32 v0, s6, 0
	s_add_u32 s2, s26, 0x39c0200
	v_mbcnt_hi_u32_b32 v0, s7, v0
	s_addc_u32 s3, s27, 0
	v_cmp_eq_u32_e32 vcc, 0, v0
	v_readlane_b32 s8, v255, 2
	v_readlane_b32 s9, v255, 17
	s_nop 0
	s_sub_i32 s9, s9, s8
	s_cmp_lg_u32 s9, 1
	s_cbranch_scc1 .Lxb_not1
	s_getreg_b32 s8, hwreg(20, 0, 4)
	s_and_b32 s8, s8, 15
	s_lshl_b32 s8, 1, s8
	v_readlane_b32 s12, v255, 9
	s_nop 0
	s_lshr_b32 s12, s12, 6
	v_mov_b32_e32 v2, s8
	v_mov_b32_e32 v1, s12
	global_atomic_or v1, v2, s[2:3] offset:2368
	s_branch .Lxb_cons
.Lxb_not1:
	s_cmp_lg_u32 s9, 2
	s_cbranch_scc1 .Lxb_ge3
	v_readlane_b32 s12, v255, 9
	s_nop 0
	s_lshr_b32 s12, s12, 6
	v_mov_b32_e32 v1, s12
	global_load_dword v1, v1, s[2:3] offset:2368 sc1
	s_waitcnt vmcnt(0)
	v_readfirstlane_b32 s8, v1
	s_nop 0
	s_bcnt1_i32_b32 s8, s8
	s_cmp_eq_u32 s8, 1
	s_cselect_b32 s100, 1, 2
	s_branch .Lxb_cons
.Lxb_ge3:
	s_cmp_eq_u32 s100, 1
	s_cbranch_scc1 .Lxb_arrive

.Lxb_arrive:
	s_and_saveexec_b64 s[8:9], vcc
	s_cbranch_execz .LBB0_2681
	s_bcnt1_i32_b64 s6, s[6:7]
	v_readlane_b32 s7, v255, 9
	v_mov_b32_e32 v2, s6
	s_nop 0
	v_mov_b32_e32 v1, s7
	global_atomic_add v1, v1, v2, s[2:3] offset:256 sc0
.LBB0_2681:
	s_or_b64 exec, exec, s[8:9]
	v_readlane_b32 s8, v255, 13
	v_readlane_b32 s6, v255, 6
	v_readlane_b32 s9, v255, 14
	s_add_i32 s6, s8, s6
	v_readlane_b32 s8, v255, 2
	v_readlane_b32 s7, v255, 17
	s_lshr_b32 s6, s6, 3
	s_sub_i32 s11, s7, s8
	s_waitcnt vmcnt(0)
	v_readfirstlane_b32 s7, v1
	s_mul_i32 s6, s6, s11
	v_readlane_b32 s9, v255, 3
	v_add3_u32 v0, s7, v0, 1
	v_cmp_eq_u32_e32 vcc, s6, v0
	s_and_saveexec_b64 s[6:7], vcc
	s_cbranch_execz .LBB0_2684
	s_mov_b64 s[8:9], exec
	v_mbcnt_lo_u32_b32 v0, s8, 0
	v_mbcnt_hi_u32_b32 v0, s9, v0
	v_cmp_eq_u32_e32 vcc, 0, v0
	s_and_b64 s[12:13], exec, vcc
	s_mov_b64 exec, s[12:13]
	s_cbranch_execz .LBB0_2684
	s_bcnt1_i32_b64 s8, s[8:9]
	v_mov_b32_e32 v0, s8
	s_cmp_eq_u32 s100, 1
	s_cbranch_scc0 .Lxb_top
	buffer_wbl2 sc1
	s_waitcnt vmcnt(0)
.Lxb_top:
	global_atomic_add v129, v0, s[2:3]
